# NSA selected-branch item loop software-pipelined by hand: next item's descriptor/Q/ref-max reads issued at top, score MFMAs for next item at the end of the current one, branch-free ref-max decode
# speedup vs baseline: 1.0099x; 1.0034x over previous
.LBB0_1399:
	s_or_b64 exec, exec, s[12:13]
	s_add_u32 s4, s16, s42
	s_addc_u32 s5, s17, s43
	s_add_u32 s50, s4, 0x4200000
	s_addc_u32 s51, s5, 0
	s_waitcnt lgkmcnt(0)
	s_barrier
	s_cmp_gt_i32 s52, 0
	v_lshrrev_b32_e32 v2, 1, v210
	s_cselect_b64 s[20:21], -1, 0
	s_cmp_lt_i32 s52, 1
	v_add_u32_e32 v1, 0, v212
	v_add_u32_e32 v184, s87, v228
	v_and_b32_e32 v185, 16, v2
	s_cbranch_scc1 .LBB0_1424
	v_mov_b32_e32 v2, s86
	ds_read_b32 v2, v2
	v_add_u32_e32 v188, s91, v185
	s_mov_b32 s53, -1
	s_waitcnt lgkmcnt(0)
	v_readfirstlane_b32 s26, v2
	s_lshl_b32 s4, s26, 13
	s_and_b32 s12, s4, 0x1fe000
	s_add_u32 s4, s48, s12
	s_addc_u32 s5, s49, 0
	s_add_u32 s12, s50, s12
	s_addc_u32 s13, s51, 0
	global_load_dwordx4 v[50:53], v194, s[4:5]
	global_load_dwordx4 v[54:57], v194, s[4:5] offset:1024
	global_load_dwordx4 v[58:61], v194, s[4:5] offset:2048
	global_load_dwordx4 v[62:65], v194, s[4:5] offset:3072
	global_load_dwordx4 v[66:69], v200, s[4:5]
	global_load_dwordx4 v[78:81], v202, s[4:5]
	global_load_dwordx4 v[90:93], v204, s[4:5]
	global_load_dwordx4 v[98:101], v206, s[4:5]
	global_load_dwordx4 v[74:77], v194, s[12:13]
	global_load_dwordx4 v[70:73], v194, s[12:13] offset:1024
	global_load_dwordx4 v[86:89], v194, s[12:13] offset:2048
	global_load_dwordx4 v[82:85], v194, s[12:13] offset:3072
	global_load_dwordx4 v[94:97], v200, s[12:13]
	global_load_dwordx4 v[102:105], v202, s[12:13]
	global_load_dwordx4 v[106:109], v204, s[12:13]
	global_load_dwordx4 v[110:113], v206, s[12:13]
	s_add_i32 s4, s53, 1
	s_add_i32 s5, s52, -1
	s_min_u32 s4, s4, s5
	s_add_i32 s23, s53, 2
	s_min_u32 s23, s23, s5
	s_lshl_b32 s23, s23, 2
	s_add_i32 s23, s86, s23
	v_mov_b32_e32 v132, s23
	ds_read_b32 v133, v132
	v_lshl_add_u32 v134, s4, 3, v184
	ds_read_u8 v135, v134
	s_and_b32 s54, s26, 0xff
	s_waitcnt lgkmcnt(0)
	v_readfirstlane_b32 s55, v133
	v_cmp_ne_u16_sdwa s[58:59], v135, s79 src0_sel:BYTE_0 src1_sel:DWORD
	s_and_b32 s4, s55, 0xff
	s_cmp_eq_u32 s4, s54
	s_cselect_b64 s[56:57], -1, 0
	v_cndmask_b32_e64 v135, 0, v135, s[58:59]
	v_and_b32_e32 v136, 0xff, v135
	v_lshl_or_b32 v130, v136, 2, v227
	v_mad_u32_u24 v137, v130, s66, v188
	ds_read_b128 v[114:117], v137
	ds_read_b128 v[118:121], v137 offset:32
	ds_read_b128 v[122:125], v137 offset:64
	ds_read_b128 v[126:129], v137 offset:96
	v_lshlrev_b32_e32 v138, 2, v130
	v_add_u32_e32 v138, 0x10400, v138
	ds_read_b32 v139, v138
	s_waitcnt lgkmcnt(0)
	s_branch .Lit_commit
.Lit_top:
	s_add_i32 s4, s53, 1
	s_add_i32 s5, s52, -1
	s_min_u32 s4, s4, s5
	s_add_i32 s23, s53, 2
	s_min_u32 s23, s23, s5
	s_lshl_b32 s23, s23, 2
	s_add_i32 s23, s86, s23
	v_mov_b32_e32 v132, s23
	ds_read_b32 v133, v132
	v_lshl_add_u32 v134, s4, 3, v184
	ds_read_u8 v135, v134
	s_and_b32 s54, s26, 0xff
	v_ashrrev_i32_e32 v141, 31, v139
	v_lshrrev_b32_e32 v141, 1, v141
	v_xor_b32_e32 v141, v139, v141
	v_cmp_eq_u32_e32 vcc, 0, v139
	v_not_b32_e32 v141, v141
	s_nop 0
	v_cndmask_b32_e32 v141, v141, v219, vcc
	v_cndmask_b32_e64 v141, 0, v141, s[14:15]
	v_add_f32_e32 v140, 0xc1200000, v141
	s_waitcnt lgkmcnt(0)
	v_readfirstlane_b32 s55, v133
	v_cmp_ne_u16_sdwa s[58:59], v135, s79 src0_sel:BYTE_0 src1_sel:DWORD
	s_and_b32 s4, s55, 0xff
	s_cmp_eq_u32 s4, s54
	s_cselect_b64 s[56:57], -1, 0
	v_cndmask_b32_e64 v135, 0, v135, s[58:59]
	v_and_b32_e32 v136, 0xff, v135
	v_lshl_or_b32 v130, v136, 2, v227
	v_mad_u32_u24 v137, v130, s66, v188
	ds_read_b128 v[114:117], v137
	ds_read_b128 v[118:121], v137 offset:32
	ds_read_b128 v[122:125], v137 offset:64
	ds_read_b128 v[126:129], v137 offset:96
	v_lshlrev_b32_e32 v138, 2, v130
	v_add_u32_e32 v138, 0x10400, v138
	ds_read_b32 v139, v138
	s_and_b64 vcc, exec, s[16:17]
	s_cbranch_vccnz .Lit_far
	s_sub_i32 s4, s44, s22
	v_lshl_add_u32 v34, s4, 6, v46
	s_nop 0
	v_sub_u32_e32 v34, v34, v181
	v_add_u32_e32 v36, -1, v34
	v_add_u32_e32 v38, -2, v34
	v_add_u32_e32 v40, -3, v34
	v_add_u32_e32 v42, -8, v34
	v_add_u32_e32 v44, -9, v34
	v_add_u32_e32 v46, -10, v34
	v_add_u32_e32 v48, -11, v34
	v_med3_i32 v35, v34, 0, v220
	v_med3_i32 v37, v36, 0, v220
	v_med3_i32 v39, v38, 0, v220
	v_med3_i32 v41, v40, 0, v220
	v_med3_i32 v43, v42, 0, v220
	v_med3_i32 v45, v44, 0, v220
	v_med3_i32 v47, v46, 0, v220
	v_med3_i32 v49, v48, 0, v220
	v_lshl_add_u32 v35, v35, 2, v180
	v_lshl_add_u32 v37, v37, 2, v180
	v_lshl_add_u32 v39, v39, 2, v180
	v_lshl_add_u32 v41, v41, 2, v180
	v_lshl_add_u32 v43, v43, 2, v180
	v_lshl_add_u32 v45, v45, 2, v180
	v_lshl_add_u32 v47, v47, 2, v180
	v_lshl_add_u32 v49, v49, 2, v180
	ds_read_b32 v35, v35
	ds_read_b32 v37, v37
	ds_read_b32 v39, v39
	ds_read_b32 v41, v41
	ds_read_b32 v43, v43
	ds_read_b32 v45, v45
	ds_read_b32 v47, v47
	ds_read_b32 v49, v49
	s_waitcnt lgkmcnt(7)
	v_add_f32_e32 v18, v18, v35
	v_cmp_lt_i32_e32 vcc, -1, v34
	v_mul_f32_e32 v18, 0x3fb8aa3b, v18
	s_and_b64 vcc, s[14:15], vcc
	v_cndmask_b32_e32 v18, v219, v18, vcc
	s_waitcnt lgkmcnt(6)
	v_add_f32_e32 v19, v19, v37
	v_cmp_lt_i32_e32 vcc, -1, v36
	v_mul_f32_e32 v19, 0x3fb8aa3b, v19
	s_and_b64 vcc, s[14:15], vcc
	v_cndmask_b32_e32 v19, v219, v19, vcc
	s_waitcnt lgkmcnt(5)
	v_add_f32_e32 v20, v20, v39
	v_cmp_lt_i32_e32 vcc, -1, v38
	v_mul_f32_e32 v20, 0x3fb8aa3b, v20
	s_and_b64 vcc, s[14:15], vcc
	v_cndmask_b32_e32 v20, v219, v20, vcc
	s_waitcnt lgkmcnt(4)
	v_add_f32_e32 v21, v21, v41
	v_cmp_lt_i32_e32 vcc, -1, v40
	v_mul_f32_e32 v21, 0x3fb8aa3b, v21
	s_and_b64 vcc, s[14:15], vcc
	v_cndmask_b32_e32 v21, v219, v21, vcc
	s_waitcnt lgkmcnt(3)
	v_add_f32_e32 v22, v22, v43
	v_cmp_lt_i32_e32 vcc, -1, v42
	v_mul_f32_e32 v22, 0x3fb8aa3b, v22
	s_and_b64 vcc, s[14:15], vcc
	v_cndmask_b32_e32 v22, v219, v22, vcc
	s_waitcnt lgkmcnt(2)
	v_add_f32_e32 v23, v23, v45
	v_cmp_lt_i32_e32 vcc, -1, v44
	v_mul_f32_e32 v23, 0x3fb8aa3b, v23
	s_and_b64 vcc, s[14:15], vcc
	v_cndmask_b32_e32 v23, v219, v23, vcc
	s_waitcnt lgkmcnt(1)
	v_add_f32_e32 v24, v24, v47
	v_cmp_lt_i32_e32 vcc, -1, v46
	v_mul_f32_e32 v24, 0x3fb8aa3b, v24
	s_and_b64 vcc, s[14:15], vcc
	s_waitcnt lgkmcnt(0)
	v_add_f32_e32 v25, v25, v49
	v_add_u32_e32 v35, -16, v34
	v_subrev_u32_e32 v37, 17, v34
	v_subrev_u32_e32 v39, 18, v34
	v_subrev_u32_e32 v41, 19, v34
	v_subrev_u32_e32 v43, 24, v34
	v_subrev_u32_e32 v45, 25, v34
	v_subrev_u32_e32 v47, 26, v34
	v_subrev_u32_e32 v49, 27, v34
	v_cndmask_b32_e32 v24, v219, v24, vcc
	v_cmp_lt_i32_e32 vcc, -1, v48
	v_med3_i32 v36, v35, 0, v220
	v_med3_i32 v38, v37, 0, v220
	v_med3_i32 v40, v39, 0, v220
	v_med3_i32 v42, v41, 0, v220
	v_med3_i32 v44, v43, 0, v220
	v_med3_i32 v46, v45, 0, v220
	v_med3_i32 v48, v47, 0, v220
	v_med3_i32 v190, v49, 0, v220
	v_mul_f32_e32 v25, 0x3fb8aa3b, v25
	s_and_b64 vcc, s[14:15], vcc
	v_lshl_add_u32 v36, v36, 2, v180
	v_lshl_add_u32 v38, v38, 2, v180
	v_lshl_add_u32 v40, v40, 2, v180
	v_lshl_add_u32 v42, v42, 2, v180
	v_lshl_add_u32 v44, v44, 2, v180
	v_lshl_add_u32 v46, v46, 2, v180
	v_lshl_add_u32 v48, v48, 2, v180
	v_lshl_add_u32 v190, v190, 2, v180
	v_cndmask_b32_e32 v25, v219, v25, vcc
	ds_read_b32 v36, v36
	ds_read_b32 v38, v38
	ds_read_b32 v40, v40
	ds_read_b32 v42, v42
	ds_read_b32 v44, v44
	ds_read_b32 v46, v46
	ds_read_b32 v48, v48
	ds_read_b32 v190, v190
	s_waitcnt lgkmcnt(7)
	v_add_f32_e32 v26, v26, v36
	v_cmp_lt_i32_e32 vcc, -1, v35
	v_mul_f32_e32 v26, 0x3fb8aa3b, v26
	s_and_b64 vcc, s[14:15], vcc
	v_cndmask_b32_e32 v26, v219, v26, vcc
	s_waitcnt lgkmcnt(6)
	v_add_f32_e32 v27, v27, v38
	v_cmp_lt_i32_e32 vcc, -1, v37
	v_mul_f32_e32 v27, 0x3fb8aa3b, v27
	s_and_b64 vcc, s[14:15], vcc
	v_cndmask_b32_e32 v27, v219, v27, vcc
	s_waitcnt lgkmcnt(5)
	v_add_f32_e32 v28, v28, v40
	v_cmp_lt_i32_e32 vcc, -1, v39
	v_mul_f32_e32 v28, 0x3fb8aa3b, v28
	s_and_b64 vcc, s[14:15], vcc
	v_cndmask_b32_e32 v28, v219, v28, vcc
	s_waitcnt lgkmcnt(4)
	v_add_f32_e32 v29, v29, v42
	v_cmp_lt_i32_e32 vcc, -1, v41
	v_mul_f32_e32 v29, 0x3fb8aa3b, v29
	s_and_b64 vcc, s[14:15], vcc
	v_cndmask_b32_e32 v29, v219, v29, vcc
	s_waitcnt lgkmcnt(3)
	v_add_f32_e32 v30, v30, v44
	v_cmp_lt_i32_e32 vcc, -1, v43
	v_mul_f32_e32 v30, 0x3fb8aa3b, v30
	s_and_b64 vcc, s[14:15], vcc
	v_cndmask_b32_e32 v30, v219, v30, vcc
	s_waitcnt lgkmcnt(2)
	v_add_f32_e32 v31, v31, v46
	v_cmp_lt_i32_e32 vcc, -1, v45
	v_mul_f32_e32 v31, 0x3fb8aa3b, v31
	s_and_b64 vcc, s[14:15], vcc
	v_cndmask_b32_e32 v31, v219, v31, vcc
	s_waitcnt lgkmcnt(1)
	v_add_f32_e32 v32, v32, v48
	v_cmp_lt_i32_e32 vcc, -1, v47
	v_mul_f32_e32 v32, 0x3fb8aa3b, v32
	s_and_b64 vcc, s[14:15], vcc
	v_cndmask_b32_e32 v32, v219, v32, vcc
	v_cmp_lt_i32_e32 vcc, -1, v49
	v_subrev_u32_e32 v35, 32, v34
	v_subrev_u32_e32 v37, 33, v34
	v_subrev_u32_e32 v39, 34, v34
	v_subrev_u32_e32 v41, 35, v34
	v_subrev_u32_e32 v43, 40, v34
	v_subrev_u32_e32 v45, 41, v34
	v_subrev_u32_e32 v47, 42, v34
	v_subrev_u32_e32 v49, 43, v34
	s_waitcnt lgkmcnt(0)
	v_add_f32_e32 v33, v33, v190
	v_med3_i32 v36, v35, 0, v220
	v_med3_i32 v38, v37, 0, v220
	v_med3_i32 v40, v39, 0, v220
	v_med3_i32 v42, v41, 0, v220
	v_med3_i32 v44, v43, 0, v220
	v_med3_i32 v46, v45, 0, v220
	v_med3_i32 v48, v47, 0, v220
	v_med3_i32 v190, v49, 0, v220
	v_mul_f32_e32 v33, 0x3fb8aa3b, v33
	s_and_b64 vcc, s[14:15], vcc
	v_lshl_add_u32 v36, v36, 2, v180
	v_lshl_add_u32 v38, v38, 2, v180
	v_lshl_add_u32 v40, v40, 2, v180
	v_lshl_add_u32 v42, v42, 2, v180
	v_lshl_add_u32 v44, v44, 2, v180
	v_lshl_add_u32 v46, v46, 2, v180
	v_lshl_add_u32 v48, v48, 2, v180
	v_lshl_add_u32 v190, v190, 2, v180
	v_cndmask_b32_e32 v33, v219, v33, vcc
	ds_read_b32 v36, v36
	ds_read_b32 v38, v38
	ds_read_b32 v40, v40
	ds_read_b32 v42, v42
	ds_read_b32 v44, v44
	ds_read_b32 v46, v46
	ds_read_b32 v48, v48
	ds_read_b32 v190, v190
	s_waitcnt lgkmcnt(7)
	v_add_f32_e32 v2, v2, v36
	v_cmp_lt_i32_e32 vcc, -1, v35
	v_mul_f32_e32 v2, 0x3fb8aa3b, v2
	s_and_b64 vcc, s[14:15], vcc
	v_cndmask_b32_e32 v2, v219, v2, vcc
	s_waitcnt lgkmcnt(6)
	v_add_f32_e32 v3, v3, v38
	v_cmp_lt_i32_e32 vcc, -1, v37
	v_mul_f32_e32 v3, 0x3fb8aa3b, v3
	s_and_b64 vcc, s[14:15], vcc
	v_cndmask_b32_e32 v3, v219, v3, vcc
	s_waitcnt lgkmcnt(5)
	v_add_f32_e32 v4, v4, v40
	v_cmp_lt_i32_e32 vcc, -1, v39
	v_mul_f32_e32 v4, 0x3fb8aa3b, v4
	s_and_b64 vcc, s[14:15], vcc
	v_cndmask_b32_e32 v4, v219, v4, vcc
	s_waitcnt lgkmcnt(4)
	v_add_f32_e32 v5, v5, v42
	v_cmp_lt_i32_e32 vcc, -1, v41
	v_mul_f32_e32 v5, 0x3fb8aa3b, v5
	s_and_b64 vcc, s[14:15], vcc
	v_cndmask_b32_e32 v5, v219, v5, vcc
	s_waitcnt lgkmcnt(3)
	v_add_f32_e32 v6, v6, v44
	v_cmp_lt_i32_e32 vcc, -1, v43
	v_mul_f32_e32 v6, 0x3fb8aa3b, v6
	s_and_b64 vcc, s[14:15], vcc
	v_cndmask_b32_e32 v6, v219, v6, vcc
	s_waitcnt lgkmcnt(2)
	v_add_f32_e32 v7, v7, v46
	v_cmp_lt_i32_e32 vcc, -1, v45
	v_mul_f32_e32 v7, 0x3fb8aa3b, v7
	s_and_b64 vcc, s[14:15], vcc
	v_cndmask_b32_e32 v7, v219, v7, vcc
	s_waitcnt lgkmcnt(1)
	v_add_f32_e32 v8, v8, v48
	v_cmp_lt_i32_e32 vcc, -1, v47
	v_mul_f32_e32 v8, 0x3fb8aa3b, v8
	s_and_b64 vcc, s[14:15], vcc
	v_subrev_u32_e32 v35, 48, v34
	v_subrev_u32_e32 v37, 49, v34
	v_subrev_u32_e32 v39, 50, v34
	v_subrev_u32_e32 v41, 51, v34
	v_subrev_u32_e32 v43, 56, v34
	v_subrev_u32_e32 v45, 57, v34
	v_subrev_u32_e32 v47, 58, v34
	v_subrev_u32_e32 v34, 59, v34
	v_cndmask_b32_e32 v8, v219, v8, vcc
	s_waitcnt lgkmcnt(0)
	v_add_f32_e32 v9, v9, v190
	v_cmp_lt_i32_e32 vcc, -1, v49
	v_med3_i32 v36, v35, 0, v220
	v_med3_i32 v38, v37, 0, v220
	v_med3_i32 v40, v39, 0, v220
	v_med3_i32 v42, v41, 0, v220
	v_med3_i32 v44, v43, 0, v220
	v_med3_i32 v46, v45, 0, v220
	v_med3_i32 v48, v47, 0, v220
	v_med3_i32 v49, v34, 0, v220
	v_mul_f32_e32 v9, 0x3fb8aa3b, v9
	s_and_b64 vcc, s[14:15], vcc
	v_lshl_add_u32 v36, v36, 2, v180
	v_lshl_add_u32 v38, v38, 2, v180
	v_lshl_add_u32 v40, v40, 2, v180
	v_lshl_add_u32 v42, v42, 2, v180
	v_lshl_add_u32 v44, v44, 2, v180
	v_lshl_add_u32 v46, v46, 2, v180
	v_lshl_add_u32 v48, v48, 2, v180
	v_lshl_add_u32 v49, v49, 2, v180
	v_cndmask_b32_e32 v9, v219, v9, vcc
	ds_read_b32 v36, v36
	ds_read_b32 v38, v38
	ds_read_b32 v40, v40
	ds_read_b32 v42, v42
	ds_read_b32 v44, v44
	ds_read_b32 v46, v46
	ds_read_b32 v48, v48
	ds_read_b32 v49, v49
	s_waitcnt lgkmcnt(7)
	v_add_f32_e32 v10, v10, v36
	v_cmp_lt_i32_e32 vcc, -1, v35
	v_mul_f32_e32 v10, 0x3fb8aa3b, v10
	s_and_b64 vcc, s[14:15], vcc
	v_cndmask_b32_e32 v10, v219, v10, vcc
	s_waitcnt lgkmcnt(6)
	v_add_f32_e32 v11, v11, v38
	v_cmp_lt_i32_e32 vcc, -1, v37
	v_mul_f32_e32 v11, 0x3fb8aa3b, v11
	s_and_b64 vcc, s[14:15], vcc
	v_cndmask_b32_e32 v11, v219, v11, vcc
	s_waitcnt lgkmcnt(5)
	v_add_f32_e32 v12, v12, v40
	v_cmp_lt_i32_e32 vcc, -1, v39
	v_mul_f32_e32 v12, 0x3fb8aa3b, v12
	s_and_b64 vcc, s[14:15], vcc
	v_cndmask_b32_e32 v12, v219, v12, vcc
	s_waitcnt lgkmcnt(4)
	v_add_f32_e32 v13, v13, v42
	v_cmp_lt_i32_e32 vcc, -1, v41
	v_mul_f32_e32 v13, 0x3fb8aa3b, v13
	s_and_b64 vcc, s[14:15], vcc
	v_cndmask_b32_e32 v13, v219, v13, vcc
	s_waitcnt lgkmcnt(3)
	v_add_f32_e32 v14, v14, v44
	v_cmp_lt_i32_e32 vcc, -1, v43
	v_mul_f32_e32 v14, 0x3fb8aa3b, v14
	s_and_b64 vcc, s[14:15], vcc
	v_cndmask_b32_e32 v14, v219, v14, vcc
	s_waitcnt lgkmcnt(2)
	v_add_f32_e32 v15, v15, v46
	v_cmp_lt_i32_e32 vcc, -1, v45
	v_mul_f32_e32 v15, 0x3fb8aa3b, v15
	s_and_b64 vcc, s[14:15], vcc
	v_cndmask_b32_e32 v15, v219, v15, vcc
	s_waitcnt lgkmcnt(1)
	v_add_f32_e32 v16, v16, v48
	v_cmp_lt_i32_e32 vcc, -1, v47
	v_mul_f32_e32 v16, 0x3fb8aa3b, v16
	s_and_b64 vcc, s[14:15], vcc
	v_cndmask_b32_e32 v16, v219, v16, vcc
	s_waitcnt lgkmcnt(0)
	v_add_f32_e32 v17, v17, v49
	v_cmp_lt_i32_e32 vcc, -1, v34
	v_mul_f32_e32 v17, 0x3fb8aa3b, v17
	s_and_b64 vcc, s[14:15], vcc
	v_cndmask_b32_e32 v17, v219, v17, vcc
.Lit_far:
	v_lshlrev_b32_e32 v190, 2, v189
	s_and_b64 vcc, exec, s[12:13]
	s_cbranch_vccnz .Lit_w0
	s_waitcnt vmcnt(8)
	s_branch .Lit_exp

.Lit_exp:
	v_cndmask_b32_e64 v35, v219, v208, s[14:15]
	v_sub_f32_e32 v35, v35, v140
	v_cndmask_b32_e64 v191, 1.0, v222, s[16:17]
	v_cndmask_b32_e64 v192, -v140, v35, s[16:17]
	v_fma_f32 v18, v18, v191, v192
	v_exp_f32_e32 v18, v18
	v_fma_f32 v19, v19, v191, v192
	v_exp_f32_e32 v19, v19
	v_fma_f32 v20, v20, v191, v192
	v_exp_f32_e32 v20, v20
	v_fma_f32 v21, v21, v191, v192
	v_exp_f32_e32 v21, v21
	v_fma_f32 v22, v22, v191, v192
	v_add_f32_e32 v34, 0, v18
	v_exp_f32_e32 v22, v22
	v_fma_f32 v23, v23, v191, v192
	v_add_f32_e32 v34, v19, v34
	v_exp_f32_e32 v23, v23
	v_fma_f32 v24, v24, v191, v192
	v_add_f32_e32 v34, v20, v34
	v_exp_f32_e32 v24, v24
	v_fma_f32 v25, v25, v191, v192
	v_add_f32_e32 v34, v21, v34
	v_exp_f32_e32 v25, v25
	v_add_f32_e32 v34, v22, v34
	v_add_f32_e32 v34, v23, v34
	v_add_f32_e32 v34, v24, v34
	v_add_f32_e32 v38, v25, v34
	v_cvt_pk_bf16_f32 v34, v18, v19
	v_cvt_pk_bf16_f32 v35, v20, v21
	v_cvt_pk_bf16_f32 v36, v22, v23
	v_cvt_pk_bf16_f32 v37, v24, v25
	v_fma_f32 v18, v26, v191, v192
	v_exp_f32_e32 v39, v18
	v_fma_f32 v18, v27, v191, v192
	v_exp_f32_e32 v40, v18
	v_fma_f32 v18, v28, v191, v192
	v_exp_f32_e32 v41, v18
	v_fma_f32 v18, v29, v191, v192
	v_exp_f32_e32 v42, v18
	v_fma_f32 v19, v30, v191, v192
	v_add_f32_e32 v18, v39, v38
	v_exp_f32_e32 v38, v19
	v_fma_f32 v19, v31, v191, v192
	v_add_f32_e32 v18, v40, v18
	v_exp_f32_e32 v43, v19
	v_fma_f32 v19, v32, v191, v192
	v_add_f32_e32 v18, v41, v18
	v_exp_f32_e32 v44, v19
	v_fma_f32 v19, v33, v191, v192
	v_add_f32_e32 v18, v42, v18
	v_exp_f32_e32 v45, v19
	v_add_f32_e32 v18, v38, v18
	v_add_f32_e32 v18, v43, v18
	v_add_f32_e32 v18, v44, v18
	v_add_f32_e32 v46, v45, v18
	v_mfma_f32_32x32x16_bf16 v[18:33], v[74:77], v[34:37], 0
	v_cvt_pk_bf16_f32 v230, v39, v40
	v_cvt_pk_bf16_f32 v231, v41, v42
	v_cvt_pk_bf16_f32 v232, v38, v43
	v_cvt_pk_bf16_f32 v233, v44, v45
	v_fma_f32 v2, v2, v191, v192
	v_exp_f32_e32 v2, v2
	v_fma_f32 v3, v3, v191, v192
	v_exp_f32_e32 v3, v3
	v_fma_f32 v4, v4, v191, v192
	v_exp_f32_e32 v4, v4
	v_fma_f32 v5, v5, v191, v192
	v_exp_f32_e32 v5, v5
	v_fma_f32 v6, v6, v191, v192
	v_mfma_f32_32x32x16_bf16 v[18:33], v[70:73], v[230:233], v[18:33]
	v_add_f32_e32 v38, v2, v46
	v_exp_f32_e32 v6, v6
	v_fma_f32 v7, v7, v191, v192
	v_add_f32_e32 v38, v3, v38
	v_exp_f32_e32 v7, v7
	v_fma_f32 v8, v8, v191, v192
	v_add_f32_e32 v38, v4, v38
	v_exp_f32_e32 v8, v8
	v_fma_f32 v9, v9, v191, v192
	v_add_f32_e32 v38, v5, v38
	v_exp_f32_e32 v9, v9
	v_add_f32_e32 v38, v6, v38
	v_add_f32_e32 v38, v7, v38
	v_add_f32_e32 v38, v8, v38
	v_cvt_pk_bf16_f32 v2, v2, v3
	v_add_f32_e32 v193, v9, v38
	v_cvt_pk_bf16_f32 v3, v4, v5
	v_cvt_pk_bf16_f32 v4, v6, v7
	v_cvt_pk_bf16_f32 v5, v8, v9
	v_mfma_f32_32x32x16_bf16 v[34:49], v[94:97], v[34:37], 0
	v_fma_f32 v6, v10, v191, v192
	v_exp_f32_e32 v6, v6
	v_fma_f32 v7, v11, v191, v192
	v_exp_f32_e32 v7, v7
	v_fma_f32 v8, v12, v191, v192
	v_exp_f32_e32 v8, v8
	v_fma_f32 v9, v13, v191, v192
	v_mfma_f32_32x32x16_bf16 v[34:49], v[102:105], v[230:233], v[34:49]
	v_exp_f32_e32 v9, v9
	v_fma_f32 v11, v14, v191, v192
	v_add_f32_e32 v10, v6, v193
	v_exp_f32_e32 v11, v11
	v_fma_f32 v12, v15, v191, v192
	v_add_f32_e32 v10, v7, v10
	v_exp_f32_e32 v12, v12
	v_mfma_f32_32x32x16_bf16 v[18:33], v[86:89], v[2:5], v[18:33]
	v_fma_f32 v13, v16, v191, v192
	v_add_f32_e32 v10, v8, v10
	v_exp_f32_e32 v13, v13
	v_fmac_f32_e32 v192, v17, v191
	v_add_f32_e32 v10, v9, v10
	v_exp_f32_e32 v14, v192
	v_add_f32_e32 v10, v11, v10
	v_mfma_f32_32x32x16_bf16 v[34:49], v[106:109], v[2:5], v[34:49]
	v_add_f32_e32 v10, v12, v10
	v_add_f32_e32 v10, v13, v10
	v_add_f32_e32 v10, v14, v10
	v_cvt_pk_bf16_f32 v6, v6, v7
	v_cvt_pk_bf16_f32 v7, v8, v9
	v_cvt_pk_bf16_f32 v8, v11, v12
	v_cvt_pk_bf16_f32 v9, v13, v14
	s_nop 1
	v_mfma_f32_32x32x16_bf16 v[18:33], v[82:85], v[6:9], v[18:33]
	v_mov_b32_e32 v2, v10
	s_nop 1
	v_permlane32_swap_b32_e32 v10, v2
	v_add_f32_e32 v2, v10, v2
	v_mfma_f32_32x32x16_bf16 v[34:49], v[110:113], v[6:9], v[34:49]
	s_and_saveexec_b64 s[16:17], s[60:61]
	s_cbranch_execz .Lit_nols
	v_cvt_i32_f32_e32 v3, v2
	v_add_u32_e32 v4, 0x10800, v190
	ds_add_u32 v4, v3
.Lit_nols:
	s_or_b64 exec, exec, s[16:17]
	v_cmp_lt_f32_e32 vcc, s80, v2
	s_and_b64 s[4:5], s[14:15], vcc
	s_and_saveexec_b64 s[16:17], s[4:5]
	s_cbranch_execz .Lit_noflag
	v_mov_b32_e32 v2, s93
	ds_write_b32 v2, v218
.Lit_noflag:
	s_or_b64 exec, exec, s[16:17]
	s_and_saveexec_b64 s[16:17], s[14:15]
	v_cvt_i32_f32_e32 v3, v18
	v_cvt_i32_f32_e32 v4, v19
	v_cvt_i32_f32_e32 v5, v20
	v_mad_u32_u24 v2, v189, s78, v1
	v_cvt_i32_f32_e32 v6, v21
	ds_add_u32 v2, v3
	ds_add_u32 v2, v4 offset:4
	ds_add_u32 v2, v5 offset:8
	ds_add_u32 v2, v6 offset:12
	v_cvt_i32_f32_e32 v3, v22
	v_cvt_i32_f32_e32 v4, v23
	v_cvt_i32_f32_e32 v5, v24
	v_cvt_i32_f32_e32 v6, v25
	ds_add_u32 v2, v3 offset:32
	ds_add_u32 v2, v4 offset:36
	ds_add_u32 v2, v5 offset:40
	ds_add_u32 v2, v6 offset:44
	v_cvt_i32_f32_e32 v3, v26
	v_cvt_i32_f32_e32 v4, v27
	v_cvt_i32_f32_e32 v5, v28
	v_cvt_i32_f32_e32 v6, v29
	ds_add_u32 v2, v3 offset:64
	ds_add_u32 v2, v4 offset:68
	ds_add_u32 v2, v5 offset:72
	ds_add_u32 v2, v6 offset:76
	v_cvt_i32_f32_e32 v3, v30
	v_cvt_i32_f32_e32 v4, v31
	v_cvt_i32_f32_e32 v5, v32
	v_cvt_i32_f32_e32 v6, v33
	ds_add_u32 v2, v3 offset:96
	ds_add_u32 v2, v4 offset:100
	ds_add_u32 v2, v5 offset:104
	ds_add_u32 v2, v6 offset:108
	v_cvt_i32_f32_e32 v3, v34
	v_cvt_i32_f32_e32 v4, v35
	v_cvt_i32_f32_e32 v5, v36
	v_cvt_i32_f32_e32 v6, v37
	ds_add_u32 v2, v3 offset:128
	ds_add_u32 v2, v4 offset:132
	ds_add_u32 v2, v5 offset:136
	ds_add_u32 v2, v6 offset:140
	v_cvt_i32_f32_e32 v3, v38
	v_cvt_i32_f32_e32 v4, v39
	v_cvt_i32_f32_e32 v5, v40
	v_cvt_i32_f32_e32 v6, v41
	ds_add_u32 v2, v3 offset:160
	ds_add_u32 v2, v4 offset:164
	ds_add_u32 v2, v5 offset:168
	ds_add_u32 v2, v6 offset:172
	v_cvt_i32_f32_e32 v3, v42
	v_cvt_i32_f32_e32 v4, v43
	v_cvt_i32_f32_e32 v5, v44
	v_cvt_i32_f32_e32 v6, v45
	ds_add_u32 v2, v3 offset:192
	ds_add_u32 v2, v4 offset:196
	ds_add_u32 v2, v5 offset:200
	ds_add_u32 v2, v6 offset:204
	v_cvt_i32_f32_e32 v3, v46
	v_cvt_i32_f32_e32 v4, v47
	v_cvt_i32_f32_e32 v5, v48
	v_cvt_i32_f32_e32 v6, v49
	ds_add_u32 v2, v3 offset:224
	ds_add_u32 v2, v4 offset:228
	ds_add_u32 v2, v5 offset:232
	ds_add_u32 v2, v6 offset:236
	s_or_b64 exec, exec, s[16:17]
	s_and_b64 vcc, exec, s[12:13]
	s_cbranch_vccnz .Lit_nov
	s_and_b32 s4, s26, 0xff
	s_lshl_b32 s4, s4, 13
	s_add_u32 s4, s50, s4
	s_addc_u32 s5, s51, 0
	global_load_dwordx4 v[74:77], v194, s[4:5]
	global_load_dwordx4 v[70:73], v194, s[4:5] offset:1024
	global_load_dwordx4 v[86:89], v194, s[4:5] offset:2048
	global_load_dwordx4 v[82:85], v194, s[4:5] offset:3072
	global_load_dwordx4 v[94:97], v200, s[4:5]
	global_load_dwordx4 v[102:105], v202, s[4:5]
	global_load_dwordx4 v[106:109], v204, s[4:5]
	global_load_dwordx4 v[110:113], v206, s[4:5]
.Lit_nov:
	s_add_i32 s4, s53, 1
	s_cmp_ge_u32 s4, s52
	s_cbranch_scc1 .LBB0_1424
.Lit_commit:
	s_add_i32 s53, s53, 1
	s_mov_b32 s22, s54
	s_mov_b32 s26, s55
	s_mov_b64 s[12:13], s[56:57]
	s_mov_b64 s[14:15], s[58:59]
	v_mov_b32_e32 v189, v130
	v_mov_b32_e32 v46, v136
	s_cmp_lt_i32 s22, s96
	s_cselect_b64 s[16:17], -1, 0
	s_and_b64 s[60:61], s[8:9], s[14:15]
	s_waitcnt vmcnt(8) lgkmcnt(15)
	v_mfma_f32_32x32x16_bf16 v[18:33], v[50:53], v[114:117], 0
	v_mfma_f32_32x32x16_bf16 v[2:17], v[66:69], v[114:117], 0
	v_mfma_f32_32x32x16_bf16 v[18:33], v[54:57], v[118:121], v[18:33]
	v_mfma_f32_32x32x16_bf16 v[2:17], v[78:81], v[118:121], v[2:17]
	v_mfma_f32_32x32x16_bf16 v[18:33], v[58:61], v[122:125], v[18:33]
	v_mfma_f32_32x32x16_bf16 v[2:17], v[90:93], v[122:125], v[2:17]
	v_mfma_f32_32x32x16_bf16 v[18:33], v[62:65], v[126:129], v[18:33]
	v_mfma_f32_32x32x16_bf16 v[2:17], v[98:101], v[126:129], v[2:17]
	s_and_b64 vcc, exec, s[12:13]
	s_cbranch_vccnz .Lit_top
	s_and_b32 s4, s26, 0xff
	s_lshl_b32 s4, s4, 13
	s_add_u32 s4, s48, s4
	s_addc_u32 s5, s49, 0
	global_load_dwordx4 v[50:53], v194, s[4:5]
	global_load_dwordx4 v[54:57], v194, s[4:5] offset:1024
	global_load_dwordx4 v[58:61], v194, s[4:5] offset:2048
	global_load_dwordx4 v[62:65], v194, s[4:5] offset:3072
	global_load_dwordx4 v[66:69], v200, s[4:5]
	global_load_dwordx4 v[78:81], v202, s[4:5]
	global_load_dwordx4 v[90:93], v204, s[4:5]
	global_load_dwordx4 v[98:101], v206, s[4:5]
	s_branch .Lit_top
